# norm+modulate phase main loop rewritten by hand (all 36-52 row loads of a wave in flight at once, no residual copy: first residual update reads x from the inputs)
# speedup vs baseline: 1.0118x; 1.0084x over previous
.LBB0_104:
	s_cmp_lt_i32 s90, 2
	s_cselect_b64 s[0:1], -1, 0
	s_add_u32 s38, s30, 0x5200000
	s_addc_u32 s39, s31, 0
	s_add_u32 s42, s30, 0x9400000
	s_addc_u32 s43, s31, 0
	s_and_b64 s[2:3], s[0:1], s[2:3]
	v_mov_b32_e32 v205, v204
	s_andn2_b64 vcc, exec, s[2:3]
	s_cbranch_vccnz .LBB0_148
	v_readlane_b32 s2, v240, 0
	s_lshl_b32 s2, s2, 3
	s_add_i32 s4, s2, s95
	s_lshl_b32 s33, s9, 3
	s_cmpk_gt_i32 s4, 0x41ff
	v_cmp_eq_u32_e64 s[2:3], 0, v176
	s_cbranch_scc1 .LBB0_122
	s_add_u32 s46, s30, 0x160000
	s_addc_u32 s47, s31, 0
	s_add_i32 s10, s4, s33
	s_ashr_i32 s11, s10, 31
	v_lshlrev_b32_e32 v48, 2, v176
	s_lshl_b32 s48, s9, 4
	s_lshl_b64 s[12:13], s[10:11], 2
	s_mul_i32 s6, s9, 24
	v_ashrrev_i32_e32 v49, 31, v48
	s_add_u32 s49, s12, 0x160000
	v_lshlrev_b64 v[0:1], 2, v[48:49]
	v_lshlrev_b64 v[2:3], 1, v[48:49]
	s_addc_u32 s56, s13, 0
	s_ashr_i32 s7, s6, 31
	s_lshl_b64 s[14:15], s[10:11], 12
	s_lshl_b64 s[16:17], s[10:11], 11
	s_ashr_i32 s5, s4, 31
	s_lshl_b64 s[12:13], s[6:7], 2
	v_lshl_add_u64 v[62:63], s[14:15], 0, v[0:1]
	s_lshl_b64 s[14:15], s[6:7], 12
	v_lshl_add_u64 v[64:65], s[16:17], 0, v[2:3]
	s_lshl_b64 s[16:17], s[6:7], 11
	s_lshl_b64 s[18:19], s[4:5], 2
	s_add_u32 s57, s18, 0x160000
	s_addc_u32 s58, s19, 0
	s_lshl_b64 s[18:19], s[4:5], 12
	v_lshl_add_u64 v[50:51], s[44:45], 0, v[0:1]
	v_add_u32_e32 v52, 0x100, v48
	v_add_u32_e32 v54, 0x200, v48
	v_add_u32_e32 v56, 0x300, v48
	v_lshl_add_u64 v[60:61], s[38:39], 0, v[0:1]
	v_lshl_add_u64 v[66:67], s[18:19], 0, v[0:1]
	s_lshl_b64 s[18:19], s[4:5], 11
	v_mbcnt_lo_u32_b32 v0, -1, 0
	v_ashrrev_i32_e32 v177, 31, v176
	v_ashrrev_i32_e32 v53, 31, v52
	v_ashrrev_i32_e32 v55, 31, v54
	v_ashrrev_i32_e32 v57, 31, v56
	v_lshl_add_u64 v[58:59], s[42:43], 0, v[2:3]
	v_lshl_add_u64 v[68:69], s[18:19], 0, v[2:3]
	s_mov_b64 s[18:19], 0
	v_mbcnt_hi_u32_b32 v70, -1, v0
	v_mov_b32_e32 v71, 0
	s_movk_i32 s59, 0x2400
	s_mov_b32 s60, 0x9400000
	s_mov_b32 s61, 0x5200000
	s_mov_b32 s62, s4
	s_cmp_lg_u32 s9, 0x100
	s_cbranch_scc1 .LBB0_109
	v_lshlrev_b32_e32 v202, 4, v176
	v_lshlrev_b32_e32 v203, 3, v176
	s_lshl_b32 s5, s8, 3
	s_add_i32 s5, s5, s95
	s_cmpk_lt_u32 s5, 0x200
	s_cselect_b32 s11, 1, 0
	s_cbranch_scc0 .Lp1_notail_ld
	s_lshl_b32 s7, s5, 12
	s_add_u32 s12, s40, s7
	s_addc_u32 s13, s41, 0
	global_load_dwordx4 v[68:71], v202, s[12:13] offset:0
	global_load_dwordx4 v[72:75], v202, s[12:13] offset:1024
	global_load_dwordx4 v[76:79], v202, s[12:13] offset:2048
	global_load_dwordx4 v[80:83], v202, s[12:13] offset:3072
.Lp1_notail_ld:
	global_load_dwordx4 v[16:19], v202, s[44:45] offset:0
	global_load_dwordx4 v[20:23], v202, s[44:45] offset:1024
	global_load_dwordx4 v[28:31], v202, s[44:45] offset:2048
	global_load_dwordx4 v[32:35], v202, s[44:45] offset:3072
	s_mov_b32 s7, 0
	s_add_u32 s14, s30, 0x1000
	s_addc_u32 s15, s31, 0
	global_load_dwordx4 v[36:39], v202, s[14:15] offset:0
	global_load_dwordx4 v[40:43], v202, s[14:15] offset:1024
	global_load_dwordx4 v[44:47], v202, s[14:15] offset:2048
	global_load_dwordx4 v[24:27], v202, s[14:15] offset:3072
	s_add_i32 s6, s5, 0x0
	s_lshl_b64 s[12:13], s[6:7], 12
	s_add_u32 s12, s12, s36
	s_addc_u32 s13, s13, s37
	global_load_dwordx4 v[88:91], v202, s[12:13] offset:0
	global_load_dwordx4 v[92:95], v202, s[12:13] offset:1024
	global_load_dwordx4 v[96:99], v202, s[12:13] offset:2048
	global_load_dwordx4 v[100:103], v202, s[12:13] offset:3072
	s_add_i32 s6, s5, 0x800
	s_lshl_b64 s[12:13], s[6:7], 12
	s_add_u32 s12, s12, s36
	s_addc_u32 s13, s13, s37
	global_load_dwordx4 v[104:107], v202, s[12:13] offset:0
	global_load_dwordx4 v[108:111], v202, s[12:13] offset:1024
	global_load_dwordx4 v[112:115], v202, s[12:13] offset:2048
	global_load_dwordx4 v[116:119], v202, s[12:13] offset:3072
	s_add_i32 s6, s5, 0x1000
	s_lshl_b64 s[12:13], s[6:7], 12
	s_add_u32 s12, s12, s36
	s_addc_u32 s13, s13, s37
	global_load_dwordx4 v[120:123], v202, s[12:13] offset:0
	global_load_dwordx4 v[124:127], v202, s[12:13] offset:1024
	global_load_dwordx4 v[128:131], v202, s[12:13] offset:2048
	global_load_dwordx4 v[132:135], v202, s[12:13] offset:3072
	s_add_i32 s6, s5, 0x1800
	s_lshl_b64 s[12:13], s[6:7], 12
	s_add_u32 s12, s12, s36
	s_addc_u32 s13, s13, s37
	global_load_dwordx4 v[136:139], v202, s[12:13] offset:0
	global_load_dwordx4 v[140:143], v202, s[12:13] offset:1024
	global_load_dwordx4 v[144:147], v202, s[12:13] offset:2048
	global_load_dwordx4 v[148:151], v202, s[12:13] offset:3072
	s_add_u32 s14, s30, 0xa000
	s_addc_u32 s15, s31, 0
	global_load_dwordx4 v[160:163], v202, s[14:15] offset:0
	global_load_dwordx4 v[164:167], v202, s[14:15] offset:1024
	global_load_dwordx4 v[168:171], v202, s[14:15] offset:2048
	global_load_dwordx4 v[172:175], v202, s[14:15] offset:3072
	s_add_i32 s6, s5, 0x2000
	s_lshl_b64 s[12:13], s[6:7], 12
	s_add_u32 s12, s12, s36
	s_addc_u32 s13, s13, s37
	global_load_dwordx4 v[152:155], v202, s[12:13] offset:0
	global_load_dwordx4 v[156:159], v202, s[12:13] offset:1024
	global_load_dwordx4 v[178:181], v202, s[12:13] offset:2048
	global_load_dwordx4 v[182:185], v202, s[12:13] offset:3072
	s_add_i32 s6, s5, 0x2800
	s_lshl_b64 s[12:13], s[6:7], 12
	s_add_u32 s12, s12, s36
	s_addc_u32 s13, s13, s37
	global_load_dwordx4 v[186:189], v202, s[12:13] offset:0
	global_load_dwordx4 v[190:193], v202, s[12:13] offset:1024
	global_load_dwordx4 v[194:197], v202, s[12:13] offset:2048
	global_load_dwordx4 v[198:201], v202, s[12:13] offset:3072
	s_add_i32 s6, s5, 0x3000
	s_lshl_b64 s[12:13], s[6:7], 12
	s_add_u32 s12, s12, s36
	s_addc_u32 s13, s13, s37
	global_load_dwordx4 v[206:209], v202, s[12:13] offset:0
	global_load_dwordx4 v[210:213], v202, s[12:13] offset:1024
	global_load_dwordx4 v[214:217], v202, s[12:13] offset:2048
	global_load_dwordx4 v[218:221], v202, s[12:13] offset:3072
	s_add_i32 s6, s5, 0x3800
	s_lshl_b64 s[12:13], s[6:7], 12
	s_add_u32 s12, s12, s36
	s_addc_u32 s13, s13, s37
	global_load_dwordx4 v[222:225], v202, s[12:13] offset:0
	global_load_dwordx4 v[226:229], v202, s[12:13] offset:1024
	global_load_dwordx4 v[230:233], v202, s[12:13] offset:2048
	global_load_dwordx4 v[234:237], v202, s[12:13] offset:3072
	s_add_u32 s14, s30, 0x13000
	s_addc_u32 s15, s31, 0
	global_load_dwordx4 v[0:3], v202, s[14:15] offset:0
	global_load_dwordx4 v[4:7], v202, s[14:15] offset:1024
	global_load_dwordx4 v[8:11], v202, s[14:15] offset:2048
	global_load_dwordx4 v[12:15], v202, s[14:15] offset:3072
	s_waitcnt vmcnt(40)
	v_fma_f32 v36, v16, v36, v16
	v_fma_f32 v37, v17, v37, v17
	v_fma_f32 v38, v18, v38, v18
	v_fma_f32 v39, v19, v39, v19
	v_fma_f32 v40, v20, v40, v20
	v_fma_f32 v41, v21, v41, v21
	v_fma_f32 v42, v22, v42, v22
	v_fma_f32 v43, v23, v43, v23
	v_fma_f32 v44, v28, v44, v28
	v_fma_f32 v45, v29, v45, v29
	v_fma_f32 v46, v30, v46, v30
	v_fma_f32 v47, v31, v47, v31
	v_fma_f32 v24, v32, v24, v32
	v_fma_f32 v25, v33, v25, v33
	v_fma_f32 v26, v34, v26, v34
	v_fma_f32 v27, v35, v27, v35
	s_waitcnt vmcnt(36)
	s_add_i32 s6, s5, 0x0
	s_lshl_b32 s7, s6, 11
	s_add_u32 s12, s42, s7
	s_addc_u32 s13, s43, 0
	s_lshl_b32 s7, s6, 2
	s_add_u32 s14, s30, s7
	s_addc_u32 s15, s31, 0
	s_add_u32 s14, s14, 0x160000
	s_addc_u32 s15, s15, 0
	v_mul_f32_e32 v84, v88, v88
	v_fmac_f32_e32 v84, v89, v89
	v_fmac_f32_e32 v84, v90, v90
	v_fmac_f32_e32 v84, v91, v91
	v_fmac_f32_e32 v84, v92, v92
	v_fmac_f32_e32 v84, v93, v93
	v_fmac_f32_e32 v84, v94, v94
	v_fmac_f32_e32 v84, v95, v95
	v_fmac_f32_e32 v84, v96, v96
	v_fmac_f32_e32 v84, v97, v97
	v_fmac_f32_e32 v84, v98, v98
	v_fmac_f32_e32 v84, v99, v99
	v_fmac_f32_e32 v84, v100, v100
	v_fmac_f32_e32 v84, v101, v101
	v_fmac_f32_e32 v84, v102, v102
	v_fmac_f32_e32 v84, v103, v103
	s_nop 1
	v_add_f32_dpp v84, v84, v84 quad_perm:[1,0,3,2] row_mask:0xf bank_mask:0xf
	s_nop 1
	v_add_f32_dpp v84, v84, v84 quad_perm:[2,3,0,1] row_mask:0xf bank_mask:0xf
	s_nop 1
	v_add_f32_dpp v84, v84, v84 row_half_mirror row_mask:0xf bank_mask:0xf
	s_nop 1
	v_add_f32_dpp v84, v84, v84 row_mirror row_mask:0xf bank_mask:0xf
	s_nop 1
	v_readlane_b32 s7, v84, 16
	v_readlane_b32 s10, v84, 32
	v_readlane_b32 s27, v84, 48
	s_nop 3
	v_add_f32_e32 v85, s7, v84
	v_add_f32_e32 v85, s10, v85
	v_add_f32_e32 v85, s27, v85
	s_mov_b64 s[2:3], exec
	s_mov_b64 exec, 1
	v_mov_b32_e32 v84, 0
	global_store_dword v84, v85, s[14:15]
	s_mov_b64 exec, s[2:3]
	v_mul_f32_e32 v88, v88, v36
	v_mul_f32_e32 v89, v89, v37
	v_mul_f32_e32 v90, v90, v38
	v_mul_f32_e32 v91, v91, v39
	v_cvt_pk_f16_f32 v238, v88, v89
	v_cvt_pk_f16_f32 v239, v90, v91
	global_store_dwordx2 v203, v[238:239], s[12:13] offset:0
	v_mul_f32_e32 v92, v92, v40
	v_mul_f32_e32 v93, v93, v41
	v_mul_f32_e32 v94, v94, v42
	v_mul_f32_e32 v95, v95, v43
	v_cvt_pk_f16_f32 v238, v92, v93
	v_cvt_pk_f16_f32 v239, v94, v95
	global_store_dwordx2 v203, v[238:239], s[12:13] offset:512
	v_mul_f32_e32 v96, v96, v44
	v_mul_f32_e32 v97, v97, v45
	v_mul_f32_e32 v98, v98, v46
	v_mul_f32_e32 v99, v99, v47
	v_cvt_pk_f16_f32 v238, v96, v97
	v_cvt_pk_f16_f32 v239, v98, v99
	global_store_dwordx2 v203, v[238:239], s[12:13] offset:1024
	v_mul_f32_e32 v100, v100, v24
	v_mul_f32_e32 v101, v101, v25
	v_mul_f32_e32 v102, v102, v26
	v_mul_f32_e32 v103, v103, v27
	v_cvt_pk_f16_f32 v238, v100, v101
	v_cvt_pk_f16_f32 v239, v102, v103
	global_store_dwordx2 v203, v[238:239], s[12:13] offset:1536
	s_waitcnt vmcnt(37)
	s_add_i32 s6, s5, 0x800
	s_lshl_b32 s7, s6, 11
	s_add_u32 s12, s42, s7
	s_addc_u32 s13, s43, 0
	s_lshl_b32 s7, s6, 2
	s_add_u32 s14, s30, s7
	s_addc_u32 s15, s31, 0
	s_add_u32 s14, s14, 0x160000
	s_addc_u32 s15, s15, 0
	v_mul_f32_e32 v84, v104, v104
	v_fmac_f32_e32 v84, v105, v105
	v_fmac_f32_e32 v84, v106, v106
	v_fmac_f32_e32 v84, v107, v107
	v_fmac_f32_e32 v84, v108, v108
	v_fmac_f32_e32 v84, v109, v109
	v_fmac_f32_e32 v84, v110, v110
	v_fmac_f32_e32 v84, v111, v111
	v_fmac_f32_e32 v84, v112, v112
	v_fmac_f32_e32 v84, v113, v113
	v_fmac_f32_e32 v84, v114, v114
	v_fmac_f32_e32 v84, v115, v115
	v_fmac_f32_e32 v84, v116, v116
	v_fmac_f32_e32 v84, v117, v117
	v_fmac_f32_e32 v84, v118, v118
	v_fmac_f32_e32 v84, v119, v119
	s_nop 1
	v_add_f32_dpp v84, v84, v84 quad_perm:[1,0,3,2] row_mask:0xf bank_mask:0xf
	s_nop 1
	v_add_f32_dpp v84, v84, v84 quad_perm:[2,3,0,1] row_mask:0xf bank_mask:0xf
	s_nop 1
	v_add_f32_dpp v84, v84, v84 row_half_mirror row_mask:0xf bank_mask:0xf
	s_nop 1
	v_add_f32_dpp v84, v84, v84 row_mirror row_mask:0xf bank_mask:0xf
	s_nop 1
	v_readlane_b32 s7, v84, 16
	v_readlane_b32 s10, v84, 32
	v_readlane_b32 s27, v84, 48
	s_nop 3
	v_add_f32_e32 v85, s7, v84
	v_add_f32_e32 v85, s10, v85
	v_add_f32_e32 v85, s27, v85
	s_mov_b64 s[2:3], exec
	s_mov_b64 exec, 1
	v_mov_b32_e32 v84, 0
	global_store_dword v84, v85, s[14:15]
	s_mov_b64 exec, s[2:3]
	v_mul_f32_e32 v104, v104, v36
	v_mul_f32_e32 v105, v105, v37
	v_mul_f32_e32 v106, v106, v38
	v_mul_f32_e32 v107, v107, v39
	v_cvt_pk_f16_f32 v238, v104, v105
	v_cvt_pk_f16_f32 v239, v106, v107
	global_store_dwordx2 v203, v[238:239], s[12:13] offset:0
	v_mul_f32_e32 v108, v108, v40
	v_mul_f32_e32 v109, v109, v41
	v_mul_f32_e32 v110, v110, v42
	v_mul_f32_e32 v111, v111, v43
	v_cvt_pk_f16_f32 v238, v108, v109
	v_cvt_pk_f16_f32 v239, v110, v111
	global_store_dwordx2 v203, v[238:239], s[12:13] offset:512
	v_mul_f32_e32 v112, v112, v44
	v_mul_f32_e32 v113, v113, v45
	v_mul_f32_e32 v114, v114, v46
	v_mul_f32_e32 v115, v115, v47
	v_cvt_pk_f16_f32 v238, v112, v113
	v_cvt_pk_f16_f32 v239, v114, v115
	global_store_dwordx2 v203, v[238:239], s[12:13] offset:1024
	v_mul_f32_e32 v116, v116, v24
	v_mul_f32_e32 v117, v117, v25
	v_mul_f32_e32 v118, v118, v26
	v_mul_f32_e32 v119, v119, v27
	v_cvt_pk_f16_f32 v238, v116, v117
	v_cvt_pk_f16_f32 v239, v118, v119
	global_store_dwordx2 v203, v[238:239], s[12:13] offset:1536
	s_waitcnt vmcnt(38)
	s_add_i32 s6, s5, 0x1000
	s_lshl_b32 s7, s6, 11
	s_add_u32 s12, s42, s7
	s_addc_u32 s13, s43, 0
	s_lshl_b32 s7, s6, 2
	s_add_u32 s14, s30, s7
	s_addc_u32 s15, s31, 0
	s_add_u32 s14, s14, 0x160000
	s_addc_u32 s15, s15, 0
	v_mul_f32_e32 v84, v120, v120
	v_fmac_f32_e32 v84, v121, v121
	v_fmac_f32_e32 v84, v122, v122
	v_fmac_f32_e32 v84, v123, v123
	v_fmac_f32_e32 v84, v124, v124
	v_fmac_f32_e32 v84, v125, v125
	v_fmac_f32_e32 v84, v126, v126
	v_fmac_f32_e32 v84, v127, v127
	v_fmac_f32_e32 v84, v128, v128
	v_fmac_f32_e32 v84, v129, v129
	v_fmac_f32_e32 v84, v130, v130
	v_fmac_f32_e32 v84, v131, v131
	v_fmac_f32_e32 v84, v132, v132
	v_fmac_f32_e32 v84, v133, v133
	v_fmac_f32_e32 v84, v134, v134
	v_fmac_f32_e32 v84, v135, v135
	s_nop 1
	v_add_f32_dpp v84, v84, v84 quad_perm:[1,0,3,2] row_mask:0xf bank_mask:0xf
	s_nop 1
	v_add_f32_dpp v84, v84, v84 quad_perm:[2,3,0,1] row_mask:0xf bank_mask:0xf
	s_nop 1
	v_add_f32_dpp v84, v84, v84 row_half_mirror row_mask:0xf bank_mask:0xf
	s_nop 1
	v_add_f32_dpp v84, v84, v84 row_mirror row_mask:0xf bank_mask:0xf
	s_nop 1
	v_readlane_b32 s7, v84, 16
	v_readlane_b32 s10, v84, 32
	v_readlane_b32 s27, v84, 48
	s_nop 3
	v_add_f32_e32 v85, s7, v84
	v_add_f32_e32 v85, s10, v85
	v_add_f32_e32 v85, s27, v85
	s_mov_b64 s[2:3], exec
	s_mov_b64 exec, 1
	v_mov_b32_e32 v84, 0
	global_store_dword v84, v85, s[14:15]
	s_mov_b64 exec, s[2:3]
	v_mul_f32_e32 v120, v120, v36
	v_mul_f32_e32 v121, v121, v37
	v_mul_f32_e32 v122, v122, v38
	v_mul_f32_e32 v123, v123, v39
	v_cvt_pk_f16_f32 v238, v120, v121
	v_cvt_pk_f16_f32 v239, v122, v123
	global_store_dwordx2 v203, v[238:239], s[12:13] offset:0
	v_mul_f32_e32 v124, v124, v40
	v_mul_f32_e32 v125, v125, v41
	v_mul_f32_e32 v126, v126, v42
	v_mul_f32_e32 v127, v127, v43
	v_cvt_pk_f16_f32 v238, v124, v125
	v_cvt_pk_f16_f32 v239, v126, v127
	global_store_dwordx2 v203, v[238:239], s[12:13] offset:512
	v_mul_f32_e32 v128, v128, v44
	v_mul_f32_e32 v129, v129, v45
	v_mul_f32_e32 v130, v130, v46
	v_mul_f32_e32 v131, v131, v47
	v_cvt_pk_f16_f32 v238, v128, v129
	v_cvt_pk_f16_f32 v239, v130, v131
	global_store_dwordx2 v203, v[238:239], s[12:13] offset:1024
	v_mul_f32_e32 v132, v132, v24
	v_mul_f32_e32 v133, v133, v25
	v_mul_f32_e32 v134, v134, v26
	v_mul_f32_e32 v135, v135, v27
	v_cvt_pk_f16_f32 v238, v132, v133
	v_cvt_pk_f16_f32 v239, v134, v135
	global_store_dwordx2 v203, v[238:239], s[12:13] offset:1536
	s_waitcnt vmcnt(39)
	s_add_i32 s6, s5, 0x1800
	s_lshl_b32 s7, s6, 11
	s_add_u32 s12, s42, s7
	s_addc_u32 s13, s43, 0
	s_lshl_b32 s7, s6, 2
	s_add_u32 s14, s30, s7
	s_addc_u32 s15, s31, 0
	s_add_u32 s14, s14, 0x160000
	s_addc_u32 s15, s15, 0
	v_mul_f32_e32 v84, v136, v136
	v_fmac_f32_e32 v84, v137, v137
	v_fmac_f32_e32 v84, v138, v138
	v_fmac_f32_e32 v84, v139, v139
	v_fmac_f32_e32 v84, v140, v140
	v_fmac_f32_e32 v84, v141, v141
	v_fmac_f32_e32 v84, v142, v142
	v_fmac_f32_e32 v84, v143, v143
	v_fmac_f32_e32 v84, v144, v144
	v_fmac_f32_e32 v84, v145, v145
	v_fmac_f32_e32 v84, v146, v146
	v_fmac_f32_e32 v84, v147, v147
	v_fmac_f32_e32 v84, v148, v148
	v_fmac_f32_e32 v84, v149, v149
	v_fmac_f32_e32 v84, v150, v150
	v_fmac_f32_e32 v84, v151, v151
	s_nop 1
	v_add_f32_dpp v84, v84, v84 quad_perm:[1,0,3,2] row_mask:0xf bank_mask:0xf
	s_nop 1
	v_add_f32_dpp v84, v84, v84 quad_perm:[2,3,0,1] row_mask:0xf bank_mask:0xf
	s_nop 1
	v_add_f32_dpp v84, v84, v84 row_half_mirror row_mask:0xf bank_mask:0xf
	s_nop 1
	v_add_f32_dpp v84, v84, v84 row_mirror row_mask:0xf bank_mask:0xf
	s_nop 1
	v_readlane_b32 s7, v84, 16
	v_readlane_b32 s10, v84, 32
	v_readlane_b32 s27, v84, 48
	s_nop 3
	v_add_f32_e32 v85, s7, v84
	v_add_f32_e32 v85, s10, v85
	v_add_f32_e32 v85, s27, v85
	s_mov_b64 s[2:3], exec
	s_mov_b64 exec, 1
	v_mov_b32_e32 v84, 0
	global_store_dword v84, v85, s[14:15]
	s_mov_b64 exec, s[2:3]
	v_mul_f32_e32 v136, v136, v36
	v_mul_f32_e32 v137, v137, v37
	v_mul_f32_e32 v138, v138, v38
	v_mul_f32_e32 v139, v139, v39
	v_cvt_pk_f16_f32 v238, v136, v137
	v_cvt_pk_f16_f32 v239, v138, v139
	global_store_dwordx2 v203, v[238:239], s[12:13] offset:0
	v_mul_f32_e32 v140, v140, v40
	v_mul_f32_e32 v141, v141, v41
	v_mul_f32_e32 v142, v142, v42
	v_mul_f32_e32 v143, v143, v43
	v_cvt_pk_f16_f32 v238, v140, v141
	v_cvt_pk_f16_f32 v239, v142, v143
	global_store_dwordx2 v203, v[238:239], s[12:13] offset:512
	v_mul_f32_e32 v144, v144, v44
	v_mul_f32_e32 v145, v145, v45
	v_mul_f32_e32 v146, v146, v46
	v_mul_f32_e32 v147, v147, v47
	v_cvt_pk_f16_f32 v238, v144, v145
	v_cvt_pk_f16_f32 v239, v146, v147
	global_store_dwordx2 v203, v[238:239], s[12:13] offset:1024
	v_mul_f32_e32 v148, v148, v24
	v_mul_f32_e32 v149, v149, v25
	v_mul_f32_e32 v150, v150, v26
	v_mul_f32_e32 v151, v151, v27
	v_cvt_pk_f16_f32 v238, v148, v149
	v_cvt_pk_f16_f32 v239, v150, v151
	global_store_dwordx2 v203, v[238:239], s[12:13] offset:1536
	s_waitcnt vmcnt(40)
	v_fma_f32 v160, v16, v160, v16
	v_fma_f32 v161, v17, v161, v17
	v_fma_f32 v162, v18, v162, v18
	v_fma_f32 v163, v19, v163, v19
	v_fma_f32 v164, v20, v164, v20
	v_fma_f32 v165, v21, v165, v21
	v_fma_f32 v166, v22, v166, v22
	v_fma_f32 v167, v23, v167, v23
	v_fma_f32 v168, v28, v168, v28
	v_fma_f32 v169, v29, v169, v29
	v_fma_f32 v170, v30, v170, v30
	v_fma_f32 v171, v31, v171, v31
	v_fma_f32 v172, v32, v172, v32
	v_fma_f32 v173, v33, v173, v33
	v_fma_f32 v174, v34, v174, v34
	v_fma_f32 v175, v35, v175, v35
	s_waitcnt vmcnt(36)
	s_add_i32 s6, s5, 0x2000
	s_lshl_b32 s7, s6, 11
	s_add_u32 s12, s42, s7
	s_addc_u32 s13, s43, 0
	s_lshl_b32 s7, s6, 2
	s_add_u32 s14, s30, s7
	s_addc_u32 s15, s31, 0
	s_add_u32 s14, s14, 0x160000
	s_addc_u32 s15, s15, 0
	v_mul_f32_e32 v84, v152, v152
	v_fmac_f32_e32 v84, v153, v153
	v_fmac_f32_e32 v84, v154, v154
	v_fmac_f32_e32 v84, v155, v155
	v_fmac_f32_e32 v84, v156, v156
	v_fmac_f32_e32 v84, v157, v157
	v_fmac_f32_e32 v84, v158, v158
	v_fmac_f32_e32 v84, v159, v159
	v_fmac_f32_e32 v84, v178, v178
	v_fmac_f32_e32 v84, v179, v179
	v_fmac_f32_e32 v84, v180, v180
	v_fmac_f32_e32 v84, v181, v181
	v_fmac_f32_e32 v84, v182, v182
	v_fmac_f32_e32 v84, v183, v183
	v_fmac_f32_e32 v84, v184, v184
	v_fmac_f32_e32 v84, v185, v185
	s_nop 1
	v_add_f32_dpp v84, v84, v84 quad_perm:[1,0,3,2] row_mask:0xf bank_mask:0xf
	s_nop 1
	v_add_f32_dpp v84, v84, v84 quad_perm:[2,3,0,1] row_mask:0xf bank_mask:0xf
	s_nop 1
	v_add_f32_dpp v84, v84, v84 row_half_mirror row_mask:0xf bank_mask:0xf
	s_nop 1
	v_add_f32_dpp v84, v84, v84 row_mirror row_mask:0xf bank_mask:0xf
	s_nop 1
	v_readlane_b32 s7, v84, 16
	v_readlane_b32 s10, v84, 32
	v_readlane_b32 s27, v84, 48
	s_nop 3
	v_add_f32_e32 v85, s7, v84
	v_add_f32_e32 v85, s10, v85
	v_add_f32_e32 v85, s27, v85
	s_mov_b64 s[2:3], exec
	s_mov_b64 exec, 1
	v_mov_b32_e32 v84, 0
	global_store_dword v84, v85, s[14:15]
	s_mov_b64 exec, s[2:3]
	v_mul_f32_e32 v152, v152, v160
	v_mul_f32_e32 v153, v153, v161
	v_mul_f32_e32 v154, v154, v162
	v_mul_f32_e32 v155, v155, v163
	v_cvt_pk_f16_f32 v238, v152, v153
	v_cvt_pk_f16_f32 v239, v154, v155
	global_store_dwordx2 v203, v[238:239], s[12:13] offset:0
	v_mul_f32_e32 v156, v156, v164
	v_mul_f32_e32 v157, v157, v165
	v_mul_f32_e32 v158, v158, v166
	v_mul_f32_e32 v159, v159, v167
	v_cvt_pk_f16_f32 v238, v156, v157
	v_cvt_pk_f16_f32 v239, v158, v159
	global_store_dwordx2 v203, v[238:239], s[12:13] offset:512
	v_mul_f32_e32 v178, v178, v168
	v_mul_f32_e32 v179, v179, v169
	v_mul_f32_e32 v180, v180, v170
	v_mul_f32_e32 v181, v181, v171
	v_cvt_pk_f16_f32 v238, v178, v179
	v_cvt_pk_f16_f32 v239, v180, v181
	global_store_dwordx2 v203, v[238:239], s[12:13] offset:1024
	v_mul_f32_e32 v182, v182, v172
	v_mul_f32_e32 v183, v183, v173
	v_mul_f32_e32 v184, v184, v174
	v_mul_f32_e32 v185, v185, v175
	v_cvt_pk_f16_f32 v238, v182, v183
	v_cvt_pk_f16_f32 v239, v184, v185
	global_store_dwordx2 v203, v[238:239], s[12:13] offset:1536
	s_waitcnt vmcnt(37)
	s_add_i32 s6, s5, 0x2800
	s_lshl_b32 s7, s6, 11
	s_add_u32 s12, s42, s7
	s_addc_u32 s13, s43, 0
	s_lshl_b32 s7, s6, 2
	s_add_u32 s14, s30, s7
	s_addc_u32 s15, s31, 0
	s_add_u32 s14, s14, 0x160000
	s_addc_u32 s15, s15, 0
	v_mul_f32_e32 v84, v186, v186
	v_fmac_f32_e32 v84, v187, v187
	v_fmac_f32_e32 v84, v188, v188
	v_fmac_f32_e32 v84, v189, v189
	v_fmac_f32_e32 v84, v190, v190
	v_fmac_f32_e32 v84, v191, v191
	v_fmac_f32_e32 v84, v192, v192
	v_fmac_f32_e32 v84, v193, v193
	v_fmac_f32_e32 v84, v194, v194
	v_fmac_f32_e32 v84, v195, v195
	v_fmac_f32_e32 v84, v196, v196
	v_fmac_f32_e32 v84, v197, v197
	v_fmac_f32_e32 v84, v198, v198
	v_fmac_f32_e32 v84, v199, v199
	v_fmac_f32_e32 v84, v200, v200
	v_fmac_f32_e32 v84, v201, v201
	s_nop 1
	v_add_f32_dpp v84, v84, v84 quad_perm:[1,0,3,2] row_mask:0xf bank_mask:0xf
	s_nop 1
	v_add_f32_dpp v84, v84, v84 quad_perm:[2,3,0,1] row_mask:0xf bank_mask:0xf
	s_nop 1
	v_add_f32_dpp v84, v84, v84 row_half_mirror row_mask:0xf bank_mask:0xf
	s_nop 1
	v_add_f32_dpp v84, v84, v84 row_mirror row_mask:0xf bank_mask:0xf
	s_nop 1
	v_readlane_b32 s7, v84, 16
	v_readlane_b32 s10, v84, 32
	v_readlane_b32 s27, v84, 48
	s_nop 3
	v_add_f32_e32 v85, s7, v84
	v_add_f32_e32 v85, s10, v85
	v_add_f32_e32 v85, s27, v85
	s_mov_b64 s[2:3], exec
	s_mov_b64 exec, 1
	v_mov_b32_e32 v84, 0
	global_store_dword v84, v85, s[14:15]
	s_mov_b64 exec, s[2:3]
	v_mul_f32_e32 v186, v186, v160
	v_mul_f32_e32 v187, v187, v161
	v_mul_f32_e32 v188, v188, v162
	v_mul_f32_e32 v189, v189, v163
	v_cvt_pk_f16_f32 v238, v186, v187
	v_cvt_pk_f16_f32 v239, v188, v189
	global_store_dwordx2 v203, v[238:239], s[12:13] offset:0
	v_mul_f32_e32 v190, v190, v164
	v_mul_f32_e32 v191, v191, v165
	v_mul_f32_e32 v192, v192, v166
	v_mul_f32_e32 v193, v193, v167
	v_cvt_pk_f16_f32 v238, v190, v191
	v_cvt_pk_f16_f32 v239, v192, v193
	global_store_dwordx2 v203, v[238:239], s[12:13] offset:512
	v_mul_f32_e32 v194, v194, v168
	v_mul_f32_e32 v195, v195, v169
	v_mul_f32_e32 v196, v196, v170
	v_mul_f32_e32 v197, v197, v171
	v_cvt_pk_f16_f32 v238, v194, v195
	v_cvt_pk_f16_f32 v239, v196, v197
	global_store_dwordx2 v203, v[238:239], s[12:13] offset:1024
	v_mul_f32_e32 v198, v198, v172
	v_mul_f32_e32 v199, v199, v173
	v_mul_f32_e32 v200, v200, v174
	v_mul_f32_e32 v201, v201, v175
	v_cvt_pk_f16_f32 v238, v198, v199
	v_cvt_pk_f16_f32 v239, v200, v201
	global_store_dwordx2 v203, v[238:239], s[12:13] offset:1536
	s_waitcnt vmcnt(38)
	s_add_i32 s6, s5, 0x3000
	s_lshl_b32 s7, s6, 11
	s_add_u32 s12, s42, s7
	s_addc_u32 s13, s43, 0
	s_lshl_b32 s7, s6, 2
	s_add_u32 s14, s30, s7
	s_addc_u32 s15, s31, 0
	s_add_u32 s14, s14, 0x160000
	s_addc_u32 s15, s15, 0
	v_mul_f32_e32 v84, v206, v206
	v_fmac_f32_e32 v84, v207, v207
	v_fmac_f32_e32 v84, v208, v208
	v_fmac_f32_e32 v84, v209, v209
	v_fmac_f32_e32 v84, v210, v210
	v_fmac_f32_e32 v84, v211, v211
	v_fmac_f32_e32 v84, v212, v212
	v_fmac_f32_e32 v84, v213, v213
	v_fmac_f32_e32 v84, v214, v214
	v_fmac_f32_e32 v84, v215, v215
	v_fmac_f32_e32 v84, v216, v216
	v_fmac_f32_e32 v84, v217, v217
	v_fmac_f32_e32 v84, v218, v218
	v_fmac_f32_e32 v84, v219, v219
	v_fmac_f32_e32 v84, v220, v220
	v_fmac_f32_e32 v84, v221, v221
	s_nop 1
	v_add_f32_dpp v84, v84, v84 quad_perm:[1,0,3,2] row_mask:0xf bank_mask:0xf
	s_nop 1
	v_add_f32_dpp v84, v84, v84 quad_perm:[2,3,0,1] row_mask:0xf bank_mask:0xf
	s_nop 1
	v_add_f32_dpp v84, v84, v84 row_half_mirror row_mask:0xf bank_mask:0xf
	s_nop 1
	v_add_f32_dpp v84, v84, v84 row_mirror row_mask:0xf bank_mask:0xf
	s_nop 1
	v_readlane_b32 s7, v84, 16
	v_readlane_b32 s10, v84, 32
	v_readlane_b32 s27, v84, 48
	s_nop 3
	v_add_f32_e32 v85, s7, v84
	v_add_f32_e32 v85, s10, v85
	v_add_f32_e32 v85, s27, v85
	s_mov_b64 s[2:3], exec
	s_mov_b64 exec, 1
	v_mov_b32_e32 v84, 0
	global_store_dword v84, v85, s[14:15]
	s_mov_b64 exec, s[2:3]
	v_mul_f32_e32 v206, v206, v160
	v_mul_f32_e32 v207, v207, v161
	v_mul_f32_e32 v208, v208, v162
	v_mul_f32_e32 v209, v209, v163
	v_cvt_pk_f16_f32 v238, v206, v207
	v_cvt_pk_f16_f32 v239, v208, v209
	global_store_dwordx2 v203, v[238:239], s[12:13] offset:0
	v_mul_f32_e32 v210, v210, v164
	v_mul_f32_e32 v211, v211, v165
	v_mul_f32_e32 v212, v212, v166
	v_mul_f32_e32 v213, v213, v167
	v_cvt_pk_f16_f32 v238, v210, v211
	v_cvt_pk_f16_f32 v239, v212, v213
	global_store_dwordx2 v203, v[238:239], s[12:13] offset:512
	v_mul_f32_e32 v214, v214, v168
	v_mul_f32_e32 v215, v215, v169
	v_mul_f32_e32 v216, v216, v170
	v_mul_f32_e32 v217, v217, v171
	v_cvt_pk_f16_f32 v238, v214, v215
	v_cvt_pk_f16_f32 v239, v216, v217
	global_store_dwordx2 v203, v[238:239], s[12:13] offset:1024
	v_mul_f32_e32 v218, v218, v172
	v_mul_f32_e32 v219, v219, v173
	v_mul_f32_e32 v220, v220, v174
	v_mul_f32_e32 v221, v221, v175
	v_cvt_pk_f16_f32 v238, v218, v219
	v_cvt_pk_f16_f32 v239, v220, v221
	global_store_dwordx2 v203, v[238:239], s[12:13] offset:1536
	s_waitcnt vmcnt(39)
	s_add_i32 s6, s5, 0x3800
	s_lshl_b32 s7, s6, 11
	s_add_u32 s12, s42, s7
	s_addc_u32 s13, s43, 0
	s_lshl_b32 s7, s6, 2
	s_add_u32 s14, s30, s7
	s_addc_u32 s15, s31, 0
	s_add_u32 s14, s14, 0x160000
	s_addc_u32 s15, s15, 0
	v_mul_f32_e32 v84, v222, v222
	v_fmac_f32_e32 v84, v223, v223
	v_fmac_f32_e32 v84, v224, v224
	v_fmac_f32_e32 v84, v225, v225
	v_fmac_f32_e32 v84, v226, v226
	v_fmac_f32_e32 v84, v227, v227
	v_fmac_f32_e32 v84, v228, v228
	v_fmac_f32_e32 v84, v229, v229
	v_fmac_f32_e32 v84, v230, v230
	v_fmac_f32_e32 v84, v231, v231
	v_fmac_f32_e32 v84, v232, v232
	v_fmac_f32_e32 v84, v233, v233
	v_fmac_f32_e32 v84, v234, v234
	v_fmac_f32_e32 v84, v235, v235
	v_fmac_f32_e32 v84, v236, v236
	v_fmac_f32_e32 v84, v237, v237
	s_nop 1
	v_add_f32_dpp v84, v84, v84 quad_perm:[1,0,3,2] row_mask:0xf bank_mask:0xf
	s_nop 1
	v_add_f32_dpp v84, v84, v84 quad_perm:[2,3,0,1] row_mask:0xf bank_mask:0xf
	s_nop 1
	v_add_f32_dpp v84, v84, v84 row_half_mirror row_mask:0xf bank_mask:0xf
	s_nop 1
	v_add_f32_dpp v84, v84, v84 row_mirror row_mask:0xf bank_mask:0xf
	s_nop 1
	v_readlane_b32 s7, v84, 16
	v_readlane_b32 s10, v84, 32
	v_readlane_b32 s27, v84, 48
	s_nop 3
	v_add_f32_e32 v85, s7, v84
	v_add_f32_e32 v85, s10, v85
	v_add_f32_e32 v85, s27, v85
	s_mov_b64 s[2:3], exec
	s_mov_b64 exec, 1
	v_mov_b32_e32 v84, 0
	global_store_dword v84, v85, s[14:15]
	s_mov_b64 exec, s[2:3]
	v_mul_f32_e32 v222, v222, v160
	v_mul_f32_e32 v223, v223, v161
	v_mul_f32_e32 v224, v224, v162
	v_mul_f32_e32 v225, v225, v163
	v_cvt_pk_f16_f32 v238, v222, v223
	v_cvt_pk_f16_f32 v239, v224, v225
	global_store_dwordx2 v203, v[238:239], s[12:13] offset:0
	v_mul_f32_e32 v226, v226, v164
	v_mul_f32_e32 v227, v227, v165
	v_mul_f32_e32 v228, v228, v166
	v_mul_f32_e32 v229, v229, v167
	v_cvt_pk_f16_f32 v238, v226, v227
	v_cvt_pk_f16_f32 v239, v228, v229
	global_store_dwordx2 v203, v[238:239], s[12:13] offset:512
	v_mul_f32_e32 v230, v230, v168
	v_mul_f32_e32 v231, v231, v169
	v_mul_f32_e32 v232, v232, v170
	v_mul_f32_e32 v233, v233, v171
	v_cvt_pk_f16_f32 v238, v230, v231
	v_cvt_pk_f16_f32 v239, v232, v233
	global_store_dwordx2 v203, v[238:239], s[12:13] offset:1024
	v_mul_f32_e32 v234, v234, v172
	v_mul_f32_e32 v235, v235, v173
	v_mul_f32_e32 v236, v236, v174
	v_mul_f32_e32 v237, v237, v175
	v_cvt_pk_f16_f32 v238, v234, v235
	v_cvt_pk_f16_f32 v239, v236, v237
	global_store_dwordx2 v203, v[238:239], s[12:13] offset:1536
	s_cmp_eq_u32 s11, 0
	s_cbranch_scc1 .Lp1_done
	s_waitcnt vmcnt(0)
	v_fma_f32 v0, v16, v0, v16
	v_fma_f32 v1, v17, v1, v17
	v_fma_f32 v2, v18, v2, v18
	v_fma_f32 v3, v19, v3, v19
	v_fma_f32 v4, v20, v4, v20
	v_fma_f32 v5, v21, v5, v21
	v_fma_f32 v6, v22, v6, v22
	v_fma_f32 v7, v23, v7, v23
	v_fma_f32 v8, v28, v8, v28
	v_fma_f32 v9, v29, v9, v29
	v_fma_f32 v10, v30, v10, v30
	v_fma_f32 v11, v31, v11, v31
	v_fma_f32 v12, v32, v12, v32
	v_fma_f32 v13, v33, v13, v33
	v_fma_f32 v14, v34, v14, v34
	v_fma_f32 v15, v35, v15, v35
	s_add_i32 s6, s5, 0x4000
	s_lshl_b32 s7, s6, 11
	s_add_u32 s12, s42, s7
	s_addc_u32 s13, s43, 0
	s_lshl_b32 s7, s6, 2
	s_add_u32 s14, s30, s7
	s_addc_u32 s15, s31, 0
	s_add_u32 s14, s14, 0x160000
	s_addc_u32 s15, s15, 0
	v_mul_f32_e32 v84, v68, v68
	v_fmac_f32_e32 v84, v69, v69
	v_fmac_f32_e32 v84, v70, v70
	v_fmac_f32_e32 v84, v71, v71
	v_fmac_f32_e32 v84, v72, v72
	v_fmac_f32_e32 v84, v73, v73
	v_fmac_f32_e32 v84, v74, v74
	v_fmac_f32_e32 v84, v75, v75
	v_fmac_f32_e32 v84, v76, v76
	v_fmac_f32_e32 v84, v77, v77
	v_fmac_f32_e32 v84, v78, v78
	v_fmac_f32_e32 v84, v79, v79
	v_fmac_f32_e32 v84, v80, v80
	v_fmac_f32_e32 v84, v81, v81
	v_fmac_f32_e32 v84, v82, v82
	v_fmac_f32_e32 v84, v83, v83
	s_nop 1
	v_add_f32_dpp v84, v84, v84 quad_perm:[1,0,3,2] row_mask:0xf bank_mask:0xf
	s_nop 1
	v_add_f32_dpp v84, v84, v84 quad_perm:[2,3,0,1] row_mask:0xf bank_mask:0xf
	s_nop 1
	v_add_f32_dpp v84, v84, v84 row_half_mirror row_mask:0xf bank_mask:0xf
	s_nop 1
	v_add_f32_dpp v84, v84, v84 row_mirror row_mask:0xf bank_mask:0xf
	s_nop 1
	v_readlane_b32 s7, v84, 16
	v_readlane_b32 s10, v84, 32
	v_readlane_b32 s27, v84, 48
	s_nop 3
	v_add_f32_e32 v85, s7, v84
	v_add_f32_e32 v85, s10, v85
	v_add_f32_e32 v85, s27, v85
	s_mov_b64 s[2:3], exec
	s_mov_b64 exec, 1
	v_mov_b32_e32 v84, 0
	global_store_dword v84, v85, s[14:15]
	s_mov_b64 exec, s[2:3]
	v_mul_f32_e32 v68, v68, v0
	v_mul_f32_e32 v69, v69, v1
	v_mul_f32_e32 v70, v70, v2
	v_mul_f32_e32 v71, v71, v3
	v_cvt_pk_f16_f32 v238, v68, v69
	v_cvt_pk_f16_f32 v239, v70, v71
	global_store_dwordx2 v203, v[238:239], s[12:13] offset:0
	v_mul_f32_e32 v72, v72, v4
	v_mul_f32_e32 v73, v73, v5
	v_mul_f32_e32 v74, v74, v6
	v_mul_f32_e32 v75, v75, v7
	v_cvt_pk_f16_f32 v238, v72, v73
	v_cvt_pk_f16_f32 v239, v74, v75
	global_store_dwordx2 v203, v[238:239], s[12:13] offset:512
	v_mul_f32_e32 v76, v76, v8
	v_mul_f32_e32 v77, v77, v9
	v_mul_f32_e32 v78, v78, v10
	v_mul_f32_e32 v79, v79, v11
	v_cvt_pk_f16_f32 v238, v76, v77
	v_cvt_pk_f16_f32 v239, v78, v79
	global_store_dwordx2 v203, v[238:239], s[12:13] offset:1024
	v_mul_f32_e32 v80, v80, v12
	v_mul_f32_e32 v81, v81, v13
	v_mul_f32_e32 v82, v82, v14
	v_mul_f32_e32 v83, v83, v15
	v_cvt_pk_f16_f32 v238, v80, v81
	v_cvt_pk_f16_f32 v239, v82, v83
	global_store_dwordx2 v203, v[238:239], s[12:13] offset:1536
.Lp1_done:
	s_branch .LBB0_122
